# P0: once-read f32 inputs (x rows for the input RMS-norm, p for the bf16 copy) loaded non-temporally
# speedup vs baseline: 1.0171x; 1.0171x over previous
; __device__ __forceinline__ void rms_row2_to_bf16(const float* x0, const float* x1, const float* g, bf16* o0, bf16* o1, int lane) {
;     const f32x4* xr0 = (const f32x4*)x0 + lane; const f32x4* xr1 = (const f32x4*)x1 + lane; const f32x4* gr = (const f32x4*)g + lane;
;     f32x4 v[8], w[8]; float s = 0.f, t = 0.f;
; #pragma unroll
;     for (int j = 0; j < 8; ++j) { v[j] = xr0[64 * j]; w[j] = xr1[64 * j]; }
; #pragma unroll
;     for (int j = 0; j < 8; ++j) { s += (v[j].x * v[j].x + v[j].y * v[j].y) + (v[j].z * v[j].z + v[j].w * v[j].w); t += (w[j].x * w[j].x + w[j].y * w[j].y) + (w[j].z * w[j].z + w[j].w * w[j].w); }
; #pragma unroll
;     for (int o = 1; o < 64; o <<= 1) { s += __shfl_xor(s, o); t += __shfl_xor(t, o); }
; __device__ __forceinline__ void p0_prologue(Frame& F, const Args& a) {
;     ...
;     for (int m = F.gw; m < M; m += 2 * F.NGW) rms_row2_to_bf16(a.in[0] + (size_t)m * DMODEL, a.in[0] + (size_t)(m + F.NGW) * DMODEL, a.in[2], XN + (size_t)m * DMODEL, XN + (size_t)(m + F.NGW) * DMODEL, F.lane);
.LBB0_123:
	s_ashr_i32 s17, s16, 31
	s_add_i32 s14, s16, s18
	s_lshl_b64 s[0:1], s[16:17], 13
	s_ashr_i32 s15, s14, 31
	v_lshl_add_u64 v[0:1], v[66:67], 0, s[0:1]
	s_lshl_b64 s[0:1], s[14:15], 13
	global_load_dwordx4 v[56:59], v[0:1], off nt
	global_load_dwordx4 v[48:51], v[0:1], off offset:1024 nt
	global_load_dwordx4 v[40:43], v[0:1], off offset:2048 nt
	v_lshl_add_u64 v[2:3], v[66:67], 0, s[0:1]
	global_load_dwordx4 v[32:35], v[0:1], off offset:3072 nt
	global_load_dwordx4 v[60:63], v[2:3], off nt
	global_load_dwordx4 v[52:55], v[2:3], off offset:1024 nt
	global_load_dwordx4 v[44:47], v[2:3], off offset:2048 nt
	v_add_co_u32_e32 v0, vcc, s2, v0
	s_waitcnt vmcnt(6)
	v_mov_b32_e32 v90, v57
	v_addc_co_u32_e32 v1, vcc, 0, v1, vcc
	global_load_dwordx4 v[28:31], v[0:1], off nt
	v_add_co_u32_e32 v4, vcc, s2, v2
	s_waitcnt vmcnt(6)
	v_mov_b32_e32 v91, v49
	v_addc_co_u32_e32 v5, vcc, 0, v3, vcc
	global_load_dwordx4 v[24:27], v[4:5], off nt
	global_load_dwordx4 v[36:39], v[2:3], off offset:3072 nt
	global_load_dwordx4 v[20:23], v[0:1], off offset:1024 nt
	global_load_dwordx4 v[16:19], v[4:5], off offset:1024 nt
	global_load_dwordx4 v[12:15], v[0:1], off offset:2048 nt
	s_nop 0
	global_load_dwordx4 v[0:3], v[0:1], off offset:3072 nt
	s_nop 0
	global_load_dwordx4 v[8:11], v[4:5], off offset:2048 nt
	s_nop 0
	global_load_dwordx4 v[4:7], v[4:5], off offset:3072 nt
	v_mov_b32_e32 v94, v59
	v_mov_b32_e32 v95, v51
	v_mov_b32_e32 v88, v56
	v_mov_b32_e32 v89, v48
	v_mov_b32_e32 v92, v58
	v_mov_b32_e32 v93, v50
	s_waitcnt vmcnt(13)
	v_pk_mul_f32 v[96:97], v[42:43], v[42:43]
	v_pk_mul_f32 v[98:99], v[40:41], v[40:41]
	v_pk_mul_f32 v[90:91], v[90:91], v[90:91]
	v_pk_mul_f32 v[94:95], v[94:95], v[94:95]
	s_waitcnt vmcnt(11)
	v_mov_b32_e32 v106, v61
	s_waitcnt vmcnt(10)
	v_mov_b32_e32 v107, v53
	v_mov_b32_e32 v110, v63
	v_mov_b32_e32 v111, v55
	v_mov_b32_e32 v104, v60
	v_mov_b32_e32 v105, v52
	v_mov_b32_e32 v108, v62
	v_mov_b32_e32 v109, v54
	v_pk_mov_b32 v[112:113], v[98:99], v[96:97] op_sel:[1,0]
	v_mov_b32_e32 v99, v97
	s_waitcnt vmcnt(9)
	v_pk_mul_f32 v[96:97], v[46:47], v[46:47]
	v_pk_mul_f32 v[114:115], v[44:45], v[44:45]
	v_pk_fma_f32 v[88:89], v[88:89], v[88:89], v[90:91]
	v_pk_fma_f32 v[90:91], v[92:93], v[92:93], v[94:95]
	v_pk_mul_f32 v[92:93], v[106:107], v[106:107]
	v_pk_mul_f32 v[94:95], v[110:111], v[110:111]
	v_pk_mov_b32 v[106:107], v[114:115], v[96:97] op_sel:[1,0]
	v_mov_b32_e32 v115, v97
	v_pk_add_f32 v[88:89], v[88:89], v[90:91]
	v_pk_fma_f32 v[90:91], v[104:105], v[104:105], v[92:93]
	v_pk_fma_f32 v[92:93], v[108:109], v[108:109], v[94:95]
	v_pk_add_f32 v[94:95], v[106:107], v[114:115]
	v_pk_add_f32 v[90:91], v[90:91], v[92:93]
	v_pk_add_f32 v[92:93], v[94:95], v[94:95] op_sel:[0,1] op_sel_hi:[1,0]
	v_pk_add_f32 v[90:91], v[90:91], v[90:91] op_sel:[0,1] op_sel_hi:[1,0]
	v_pk_add_f32 v[98:99], v[112:113], v[98:99]
	v_mul_f32_e32 v100, v33, v33
	v_mul_f32_e32 v102, v35, v35
	v_pk_add_f32 v[96:97], v[98:99], v[98:99] op_sel:[0,1] op_sel_hi:[1,0]
	v_pk_add_f32 v[88:89], v[88:89], v[88:89] op_sel:[0,1] op_sel_hi:[1,0]
	v_pk_fma_f32 v[100:101], v[32:33], v[32:33], v[100:101] op_sel_hi:[1,1,0]
	v_pk_fma_f32 v[102:103], v[34:35], v[34:35], v[102:103] op_sel_hi:[1,1,0]
	s_waitcnt vmcnt(7)
	v_mul_f32_e32 v110, v24, v24
	v_mul_f32_e32 v111, v25, v25
	v_mov_b32_e32 v91, v110
	v_mov_b32_e32 v93, v111
	v_pk_add_f32 v[90:91], v[90:91], v[92:93]
	s_waitcnt vmcnt(6)
	v_mul_f32_e32 v92, v37, v37
	v_mul_f32_e32 v94, v39, v39
	v_mul_f32_e32 v112, v26, v26
	v_mul_f32_e32 v113, v27, v27
	v_pk_fma_f32 v[92:93], v[36:37], v[36:37], v[92:93] op_sel_hi:[1,1,0]
	v_pk_fma_f32 v[94:95], v[38:39], v[38:39], v[94:95] op_sel_hi:[1,1,0]
	v_mov_b32_e32 v93, v112
	v_mov_b32_e32 v95, v113
	v_mul_f32_e32 v116, v28, v28
	v_mul_f32_e32 v117, v29, v29
	v_pk_add_f32 v[92:93], v[92:93], v[94:95]
	v_mul_f32_e32 v118, v30, v30
	v_mul_f32_e32 v119, v31, v31
	v_mov_b32_e32 v97, v117
	v_mov_b32_e32 v89, v116
	v_pk_add_f32 v[90:91], v[90:91], v[92:93]
	s_waitcnt vmcnt(5)
	v_pk_mul_f32 v[92:93], v[22:23], v[22:23]
	v_pk_mul_f32 v[94:95], v[20:21], v[20:21]
	v_mov_b32_e32 v101, v118
	v_mov_b32_e32 v103, v119
	v_pk_add_f32 v[88:89], v[88:89], v[96:97]
	v_pk_mov_b32 v[96:97], v[94:95], v[92:93] op_sel:[1,0]
	v_mov_b32_e32 v95, v93
	v_pk_add_f32 v[98:99], v[100:101], v[102:103]
	v_pk_add_f32 v[92:93], v[96:97], v[94:95]
	s_waitcnt vmcnt(4)
	v_pk_mul_f32 v[94:95], v[18:19], v[18:19]
	v_pk_mul_f32 v[96:97], v[16:17], v[16:17]
	v_pk_add_f32 v[88:89], v[88:89], v[98:99]
	v_pk_mov_b32 v[98:99], v[96:97], v[94:95] op_sel:[1,0]
	v_mov_b32_e32 v97, v95
	v_pk_add_f32 v[94:95], v[98:99], v[96:97]
	s_waitcnt vmcnt(2)
	v_mul_f32_e32 v96, v0, v0
	v_mul_f32_e32 v97, v1, v1
	v_pk_add_f32 v[88:89], v[88:89], v[88:89] op_sel:[0,1] op_sel_hi:[1,0]
	v_pk_add_f32 v[92:93], v[92:93], v[92:93] op_sel:[0,1] op_sel_hi:[1,0]
	v_mov_b32_e32 v89, v96
	v_mov_b32_e32 v93, v97
	v_pk_add_f32 v[88:89], v[88:89], v[92:93]
	v_mul_f32_e32 v92, v13, v13
	v_mul_f32_e32 v96, v15, v15
	v_mul_f32_e32 v98, v2, v2
	v_mul_f32_e32 v99, v3, v3
	v_pk_fma_f32 v[92:93], v[12:13], v[12:13], v[92:93] op_sel_hi:[1,1,0]
	v_pk_fma_f32 v[96:97], v[14:15], v[14:15], v[96:97] op_sel_hi:[1,1,0]
	v_mov_b32_e32 v93, v98
	v_mov_b32_e32 v97, v99
	v_pk_add_f32 v[92:93], v[92:93], v[96:97]
	s_waitcnt vmcnt(0)
	v_mul_f32_e32 v97, v6, v6
	v_pk_add_f32 v[88:89], v[88:89], v[92:93]
	v_mul_f32_e32 v92, v4, v4
	v_add_f32_e32 v96, v88, v89
	v_pk_add_f32 v[88:89], v[90:91], v[90:91] op_sel:[0,1] op_sel_hi:[1,0]
	v_pk_add_f32 v[90:91], v[94:95], v[94:95] op_sel:[0,1] op_sel_hi:[1,0]
	ds_bpermute_b32 v94, v80, v96
	v_mul_f32_e32 v93, v5, v5
	v_mov_b32_e32 v89, v92
	v_mov_b32_e32 v91, v93
	v_pk_add_f32 v[88:89], v[88:89], v[90:91]
	s_waitcnt lgkmcnt(0)
; __device__ __forceinline__ unsigned pk2(float lo, float hi) { f32x2_ v = {lo, hi}; return __builtin_bit_cast(unsigned, __builtin_convertvector(v, bf16x2_)); }
; __device__ __forceinline__ void rms_row2_to_bf16(const float* x0, const float* x1, const float* g, bf16* o0, bf16* o1, int lane) {
;     ...
;     for (int o = 1; o < 64; o <<= 1) { s += __shfl_xor(s, o); t += __shfl_xor(t, o); }
;     const float r0 = 1.f / sqrtf(s * (1.f / DMODEL) + RMS_EPS), r1 = 1.f / sqrtf(t * (1.f / DMODEL) + RMS_EPS);
;     v2u* p0 = (v2u*)o0 + lane; v2u* p1 = (v2u*)o1 + lane;
; #pragma unroll
;     for (int j = 0; j < 8; ++j) { const f32x4 gg = gr[64 * j]; const f32x4 a0 = v[j] * r0 * gg, a1 = w[j] * r1 * gg; v2u q0, q1; q0.x = pk2(a0.x, a0.y); q0.y = pk2(a0.z, a0.w); q1.x = pk2(a1.x, a1.y); q1.y = pk2(a1.z, a1.w); p0[64 * j] = q0; p1[64 * j] = q1; }
	v_add_f32_e32 v94, v96, v94
	v_mul_f32_e32 v90, v9, v9
	v_mul_f32_e32 v92, v11, v11
	ds_bpermute_b32 v95, v81, v94
	v_mul_f32_e32 v98, v7, v7
	v_pk_fma_f32 v[90:91], v[8:9], v[8:9], v[90:91] op_sel_hi:[1,1,0]
	v_pk_fma_f32 v[92:93], v[10:11], v[10:11], v[92:93] op_sel_hi:[1,1,0]
	v_mov_b32_e32 v91, v97
	v_mov_b32_e32 v93, v98
	v_pk_add_f32 v[90:91], v[90:91], v[92:93]
	s_nop 0
	v_pk_add_f32 v[88:89], v[88:89], v[90:91]
	s_waitcnt lgkmcnt(0)
	v_add_f32_e32 v90, v94, v95
	v_add_f32_e32 v88, v88, v89
	ds_bpermute_b32 v89, v80, v88
	ds_bpermute_b32 v91, v82, v90
	s_waitcnt lgkmcnt(1)
	v_add_f32_e32 v88, v88, v89
	s_waitcnt lgkmcnt(0)
	v_add_f32_e32 v90, v90, v91
	ds_bpermute_b32 v89, v81, v88
	ds_bpermute_b32 v91, v83, v90
	s_waitcnt lgkmcnt(1)
	v_add_f32_e32 v88, v88, v89
	s_waitcnt lgkmcnt(0)
	v_add_f32_e32 v90, v90, v91
	ds_bpermute_b32 v89, v82, v88
	ds_bpermute_b32 v91, v84, v90
	s_waitcnt lgkmcnt(1)
	v_add_f32_e32 v92, v88, v89
	s_waitcnt lgkmcnt(0)
	v_add_f32_e32 v94, v90, v91
	global_load_dwordx4 v[88:91], v[68:69], off nt
	ds_bpermute_b32 v95, v85, v94
	ds_bpermute_b32 v93, v83, v92
	s_waitcnt lgkmcnt(1)
	v_add_f32_e32 v94, v94, v95
	v_fmamk_f32 v94, v94, 0x3a000000, v86
	v_mul_f32_e32 v95, 0x4f800000, v94
	v_cmp_gt_f32_e32 vcc, s3, v94
	s_waitcnt lgkmcnt(0)
	v_add_f32_e32 v92, v92, v93
	ds_bpermute_b32 v93, v84, v92
	v_cndmask_b32_e32 v94, v94, v95, vcc
	v_sqrt_f32_e32 v95, v94
	s_waitcnt lgkmcnt(0)
	v_add_f32_e32 v92, v92, v93
	v_add_u32_e32 v96, -1, v95
	v_fma_f32 v97, -v96, v95, v94
	v_cmp_ge_f32_e64 s[0:1], 0, v97
	v_add_u32_e32 v97, 1, v95
	ds_bpermute_b32 v93, v85, v92
	v_cndmask_b32_e64 v96, v95, v96, s[0:1]
	v_fma_f32 v95, -v97, v95, v94
	v_cmp_lt_f32_e64 s[0:1], 0, v95
	s_waitcnt lgkmcnt(0)
	v_add_f32_e32 v92, v92, v93
	v_cndmask_b32_e64 v95, v96, v97, s[0:1]
	v_mul_f32_e32 v96, 0x37800000, v95
	v_cndmask_b32_e32 v95, v95, v96, vcc
	v_cmp_class_f32_e32 vcc, v94, v87
	v_fmamk_f32 v92, v92, 0x3a000000, v86
	v_mul_f32_e32 v98, 0x4f800000, v92
	v_cndmask_b32_e32 v94, v95, v94, vcc
	v_div_scale_f32 v95, s[0:1], v94, v94, 1.0
	v_rcp_f32_e32 v96, v95
	v_cmp_gt_f32_e64 s[0:1], s3, v92
	v_fma_f32 v93, -v95, v96, 1.0
	s_nop 0
	v_cndmask_b32_e64 v92, v92, v98, s[0:1]
	v_fmac_f32_e32 v96, v93, v96
	v_div_scale_f32 v93, vcc, 1.0, v94, 1.0
	v_sqrt_f32_e32 v98, v92
	v_mul_f32_e32 v97, v93, v96
	v_fma_f32 v99, -v95, v97, v93
	v_fmac_f32_e32 v97, v99, v96
	v_fma_f32 v93, -v95, v97, v93
	v_add_u32_e32 v95, -1, v98
	v_fma_f32 v99, -v95, v98, v92
	v_cmp_ge_f32_e64 s[4:5], 0, v99
	v_add_u32_e32 v99, 1, v98
	s_nop 0
	v_cndmask_b32_e64 v95, v98, v95, s[4:5]
	v_fma_f32 v98, -v99, v98, v92
	v_cmp_lt_f32_e64 s[4:5], 0, v98
	s_nop 1
	v_cndmask_b32_e64 v95, v95, v99, s[4:5]
	v_mul_f32_e32 v98, 0x37800000, v95
	v_cndmask_b32_e64 v95, v95, v98, s[0:1]
	v_cmp_class_f32_e64 s[0:1], v92, v87
	s_nop 1
	v_cndmask_b32_e64 v95, v95, v92, s[0:1]
	v_div_scale_f32 v98, s[0:1], v95, v95, 1.0
	v_rcp_f32_e32 v99, v98
	v_div_fmas_f32 v92, v93, v96, v97
	v_div_fixup_f32 v92, v92, v94, 1.0
	s_lshl_b64 s[0:1], s[16:17], 12
	v_fma_f32 v93, -v98, v99, 1.0
	v_fmac_f32_e32 v99, v93, v99
	v_div_scale_f32 v93, vcc, 1.0, v95, 1.0
	v_mul_f32_e32 v94, v93, v99
	v_fma_f32 v96, -v98, v94, v93
	v_fmac_f32_e32 v94, v96, v99
	v_fma_f32 v93, -v98, v94, v93
	v_div_fmas_f32 v93, v93, v99, v94
	v_div_fixup_f32 v94, v93, v95, 1.0
	v_pk_mul_f32 v[56:57], v[56:57], v[92:93] op_sel_hi:[1,0]
	v_pk_mul_f32 v[58:59], v[58:59], v[92:93] op_sel_hi:[1,0]
	s_waitcnt vmcnt(0)
; __device__ __forceinline__ unsigned pk2(float lo, float hi) { f32x2_ v = {lo, hi}; return __builtin_bit_cast(unsigned, __builtin_convertvector(v, bf16x2_)); }
; __device__ __forceinline__ void rms_row2_to_bf16(const float* x0, const float* x1, const float* g, bf16* o0, bf16* o1, int lane) {
;     ...
;     v2u* p0 = (v2u*)o0 + lane; v2u* p1 = (v2u*)o1 + lane;
; #pragma unroll
;     for (int j = 0; j < 8; ++j) { const f32x4 gg = gr[64 * j]; const f32x4 a0 = v[j] * r0 * gg, a1 = w[j] * r1 * gg; v2u q0, q1; q0.x = pk2(a0.x, a0.y); q0.y = pk2(a0.z, a0.w); q1.x = pk2(a1.x, a1.y); q1.y = pk2(a1.z, a1.w); p0[64 * j] = q0; p1[64 * j] = q1; }
	v_pk_mul_f32 v[56:57], v[88:89], v[56:57]
	v_pk_mul_f32 v[58:59], v[90:91], v[58:59]
	v_pk_mul_f32 v[60:61], v[60:61], v[94:95] op_sel_hi:[1,0]
	v_pk_mul_f32 v[62:63], v[62:63], v[94:95] op_sel_hi:[1,0]
	v_lshl_add_u64 v[96:97], v[70:71], 0, s[0:1]
	s_lshl_b64 s[0:1], s[14:15], 12
	v_pk_mul_f32 v[62:63], v[90:91], v[62:63]
	v_pk_mul_f32 v[60:61], v[88:89], v[60:61]
	v_cvt_pk_bf16_f32 v56, v56, v57
	v_cvt_pk_bf16_f32 v57, v58, v59
	v_lshl_add_u64 v[98:99], v[70:71], 0, s[0:1]
	v_cvt_pk_bf16_f32 v58, v60, v61
	v_cvt_pk_bf16_f32 v59, v62, v63
	global_store_dwordx2 v[96:97], v[56:57], off
	global_store_dwordx2 v[98:99], v[58:59], off
	global_load_dwordx4 v[56:59], v[68:69], off offset:1024 nt
	v_pk_mul_f32 v[48:49], v[48:49], v[92:93] op_sel_hi:[1,0]
	v_pk_mul_f32 v[50:51], v[50:51], v[92:93] op_sel_hi:[1,0]
	v_pk_mul_f32 v[52:53], v[52:53], v[94:95] op_sel_hi:[1,0]
	v_pk_mul_f32 v[54:55], v[54:55], v[94:95] op_sel_hi:[1,0]
	v_pk_mul_f32 v[40:41], v[40:41], v[92:93] op_sel_hi:[1,0]
	v_pk_mul_f32 v[42:43], v[42:43], v[92:93] op_sel_hi:[1,0]
	v_pk_mul_f32 v[44:45], v[44:45], v[94:95] op_sel_hi:[1,0]
	v_pk_mul_f32 v[46:47], v[46:47], v[94:95] op_sel_hi:[1,0]
	v_pk_mul_f32 v[32:33], v[32:33], v[92:93] op_sel_hi:[1,0]
	v_pk_mul_f32 v[34:35], v[34:35], v[92:93] op_sel_hi:[1,0]
	v_pk_mul_f32 v[36:37], v[36:37], v[94:95] op_sel_hi:[1,0]
	v_pk_mul_f32 v[38:39], v[38:39], v[94:95] op_sel_hi:[1,0]
	v_pk_mul_f32 v[28:29], v[28:29], v[92:93] op_sel_hi:[1,0]
	v_pk_mul_f32 v[30:31], v[30:31], v[92:93] op_sel_hi:[1,0]
	v_pk_mul_f32 v[24:25], v[24:25], v[94:95] op_sel_hi:[1,0]
	v_pk_mul_f32 v[26:27], v[26:27], v[94:95] op_sel_hi:[1,0]
	v_pk_mul_f32 v[20:21], v[20:21], v[92:93] op_sel_hi:[1,0]
	v_pk_mul_f32 v[22:23], v[22:23], v[92:93] op_sel_hi:[1,0]
	v_pk_mul_f32 v[16:17], v[16:17], v[94:95] op_sel_hi:[1,0]
	v_pk_mul_f32 v[18:19], v[18:19], v[94:95] op_sel_hi:[1,0]
	v_pk_mul_f32 v[12:13], v[12:13], v[92:93] op_sel_hi:[1,0]
	v_pk_mul_f32 v[14:15], v[14:15], v[92:93] op_sel_hi:[1,0]
	v_pk_mul_f32 v[8:9], v[8:9], v[94:95] op_sel_hi:[1,0]
	v_pk_mul_f32 v[10:11], v[10:11], v[94:95] op_sel_hi:[1,0]
	v_pk_mul_f32 v[0:1], v[0:1], v[92:93] op_sel_hi:[1,0]
	v_pk_mul_f32 v[2:3], v[2:3], v[92:93] op_sel_hi:[1,0]
	s_add_i32 s16, s14, s18
	v_pk_mul_f32 v[4:5], v[4:5], v[94:95] op_sel_hi:[1,0]
	v_pk_mul_f32 v[6:7], v[6:7], v[94:95] op_sel_hi:[1,0]
	s_cmpk_gt_i32 s16, 0x3fff
	s_waitcnt vmcnt(0)
	v_pk_mul_f32 v[50:51], v[58:59], v[50:51]
	v_pk_mul_f32 v[48:49], v[56:57], v[48:49]
	v_pk_mul_f32 v[54:55], v[58:59], v[54:55]
	v_pk_mul_f32 v[52:53], v[56:57], v[52:53]
	v_cvt_pk_bf16_f32 v48, v48, v49
	v_cvt_pk_bf16_f32 v49, v50, v51
	v_cvt_pk_bf16_f32 v50, v52, v53
	v_cvt_pk_bf16_f32 v51, v54, v55
	global_store_dwordx2 v[96:97], v[48:49], off offset:512
	global_store_dwordx2 v[98:99], v[50:51], off offset:512
	global_load_dwordx4 v[48:51], v[68:69], off offset:2048 nt
	s_waitcnt vmcnt(0)
	v_pk_mul_f32 v[42:43], v[50:51], v[42:43]
	v_pk_mul_f32 v[40:41], v[48:49], v[40:41]
	v_pk_mul_f32 v[46:47], v[50:51], v[46:47]
	v_pk_mul_f32 v[44:45], v[48:49], v[44:45]
	v_cvt_pk_bf16_f32 v40, v40, v41
	v_cvt_pk_bf16_f32 v41, v42, v43
	v_cvt_pk_bf16_f32 v42, v44, v45
	v_cvt_pk_bf16_f32 v43, v46, v47
	global_store_dwordx2 v[96:97], v[40:41], off offset:1024
	global_store_dwordx2 v[98:99], v[42:43], off offset:1024
	global_load_dwordx4 v[40:43], v[68:69], off offset:3072 nt
	s_waitcnt vmcnt(0)
	v_pk_mul_f32 v[34:35], v[34:35], v[42:43]
	v_pk_mul_f32 v[32:33], v[32:33], v[40:41]
	v_pk_mul_f32 v[38:39], v[38:39], v[42:43]
	v_pk_mul_f32 v[36:37], v[36:37], v[40:41]
	v_cvt_pk_bf16_f32 v32, v32, v33
	v_cvt_pk_bf16_f32 v33, v34, v35
	v_cvt_pk_bf16_f32 v34, v36, v37
	v_cvt_pk_bf16_f32 v35, v38, v39
	global_store_dwordx2 v[96:97], v[32:33], off offset:1536
	global_store_dwordx2 v[98:99], v[34:35], off offset:1536
	global_load_dwordx4 v[32:35], v[72:73], off nt
	s_waitcnt vmcnt(0)
	v_pk_mul_f32 v[30:31], v[30:31], v[34:35]
	v_pk_mul_f32 v[28:29], v[28:29], v[32:33]
	v_pk_mul_f32 v[26:27], v[26:27], v[34:35]
	v_pk_mul_f32 v[24:25], v[24:25], v[32:33]
	v_cvt_pk_bf16_f32 v28, v28, v29
	v_cvt_pk_bf16_f32 v29, v30, v31
	v_cvt_pk_bf16_f32 v24, v24, v25
	v_cvt_pk_bf16_f32 v25, v26, v27
	global_store_dwordx2 v[96:97], v[28:29], off offset:2048
	global_store_dwordx2 v[98:99], v[24:25], off offset:2048
	global_load_dwordx4 v[24:27], v[74:75], off nt
	s_waitcnt vmcnt(0)
	v_pk_mul_f32 v[22:23], v[22:23], v[26:27]
	v_pk_mul_f32 v[20:21], v[20:21], v[24:25]
	v_pk_mul_f32 v[18:19], v[18:19], v[26:27]
	v_pk_mul_f32 v[16:17], v[16:17], v[24:25]
	v_cvt_pk_bf16_f32 v20, v20, v21
	v_cvt_pk_bf16_f32 v21, v22, v23
	v_cvt_pk_bf16_f32 v16, v16, v17
	v_cvt_pk_bf16_f32 v17, v18, v19
	global_store_dwordx2 v[96:97], v[20:21], off offset:2560
	global_store_dwordx2 v[98:99], v[16:17], off offset:2560
	global_load_dwordx4 v[16:19], v[76:77], off nt
	s_waitcnt vmcnt(0)
	v_pk_mul_f32 v[14:15], v[14:15], v[18:19]
	v_pk_mul_f32 v[12:13], v[12:13], v[16:17]
	v_pk_mul_f32 v[10:11], v[10:11], v[18:19]
	v_pk_mul_f32 v[8:9], v[8:9], v[16:17]
	v_cvt_pk_bf16_f32 v12, v12, v13
	v_cvt_pk_bf16_f32 v13, v14, v15
	v_cvt_pk_bf16_f32 v8, v8, v9
	v_cvt_pk_bf16_f32 v9, v10, v11
	global_store_dwordx2 v[96:97], v[12:13], off offset:3072
	global_store_dwordx2 v[98:99], v[8:9], off offset:3072
	global_load_dwordx4 v[8:11], v[78:79], off nt
	s_waitcnt vmcnt(0)
	v_pk_mul_f32 v[2:3], v[2:3], v[10:11]
	v_pk_mul_f32 v[0:1], v[0:1], v[8:9]
	v_pk_mul_f32 v[6:7], v[6:7], v[10:11]
	v_pk_mul_f32 v[4:5], v[4:5], v[8:9]
	v_cvt_pk_bf16_f32 v0, v0, v1
	v_cvt_pk_bf16_f32 v1, v2, v3
	v_cvt_pk_bf16_f32 v2, v4, v5
	v_cvt_pk_bf16_f32 v3, v6, v7
	global_store_dwordx2 v[96:97], v[0:1], off offset:3584
	global_store_dwordx2 v[98:99], v[2:3], off offset:3584
	s_cbranch_scc0 .LBB0_123

; __device__ __forceinline__ unsigned pk2(float lo, float hi) { f32x2_ v = {lo, hi}; return __builtin_bit_cast(unsigned, __builtin_convertvector(v, bf16x2_)); }
; __device__ __forceinline__ void p0_prologue(Frame& F, const Args& a) {
;     ...
;     { const f32x4* p4 = (const f32x4*)a.in[1]; v4u* o = (v4u*)(ws + WS_PB); const int n8 = M * DPLE / 8;
;       for (int i = F.gw * 64 + F.lane; i < n8; i += F.NGW * 64) { const f32x4 u0 = p4[2 * i], u1 = p4[2 * i + 1]; v4u w; w.x = pk2(u0.x, u0.y); w.y = pk2(u0.z, u0.w); w.z = pk2(u1.x, u1.y); w.w = pk2(u1.z, u1.w); o[i] = w; } }
.LBB0_126:
	v_ashrrev_i32_e32 v3, 31, v2
	v_lshl_add_u64 v[8:9], v[2:3], 4, s[70:71]
	global_load_dwordx4 v[4:7], v[8:9], off nt
	s_nop 0
	global_load_dwordx4 v[8:11], v[8:9], off offset:16 nt
	v_add_u32_e32 v64, s2, v64
	v_cmp_lt_i32_e32 vcc, s16, v64
	v_add_u32_e32 v2, s3, v2
	s_or_b64 s[14:15], vcc, s[14:15]
	s_waitcnt vmcnt(1)
	v_cvt_pk_bf16_f32 v4, v4, v5
	v_cvt_pk_bf16_f32 v5, v6, v7
	s_waitcnt vmcnt(0)
	v_cvt_pk_bf16_f32 v6, v8, v9
	v_cvt_pk_bf16_f32 v7, v10, v11
	global_store_dwordx4 v[0:1], v[4:7], off
	v_lshl_add_u64 v[0:1], v[0:1], 0, s[4:5]
	s_andn2_b64 exec, exec, s[14:15]
	s_cbranch_execnz .LBB0_126
